# rstd LDS stash (both epilogues, in-proj hit path also drains vmcnt like the original) + 64-bit accumulator zeroing
# baseline (speedup 1.0000x reference)
; __device__ __forceinline__ void tile_rstd(float (&rs)[2][4], const float* ssp, int rowtile, int wr, int fr, int fq) {
;     const int lane = fq * 16 + fr; f32x4 pa[2][4][2];
; #pragma unroll
;     for (int ai = 0; ai < 2; ++ai)
; #pragma unroll
;         for (int m = 0; m < 4; ++m) { const f32x4* p = (const f32x4*)(ssp + (size_t)(rowtile + wr * 64 + ai * HALF + m * 16 + (lane >> 2)) * 32 + (lane & 3) * 8); pa[ai][m][0] = p[0]; pa[ai][m][1] = p[1]; }
; #pragma unroll
;     for (int ai = 0; ai < 2; ++ai)
; #pragma unroll
;         for (int m = 0; m < 4; ++m) { const f32x4 a = pa[ai][m][0], b = pa[ai][m][1];
;             float t = ((a.x + a.y) + (a.z + a.w)) + ((b.x + b.y) + (b.z + b.w));
;             t += __shfl_xor(t, 1); t += __shfl_xor(t, 2);
;             rs[ai][m] = __shfl(rsqrtf(t * (1.0f / 2048.0f) + 1e-6f), fr * 4); }
;     __device__ __forceinline__ void operator()(const f32x4 (&acc)[2][2][4][2], const Unit& u, int wr, int wc, int fr, int fq) const {
;         const int row0 = u.pm * BM + wr * 64 + fr; const int col0 = u.pn * BM + wc * 32 + 8 * fq;
;         float rsa[2][4];
; #pragma unroll
;         for (int ai = 0; ai < 2; ++ai)
; #pragma unroll
;             for (int m = 0; m < 4; ++m) rsa[ai][m] = 1.0f;
;         if (ss) tile_rstd(rsa, ss, u.pm * BM, wr, fr, fq);
.Lst_hit:
	v_lshrrev_b32_e32 v133, 6, v216
	v_and_b32_e32 v131, 15, v216
	v_lshlrev_b32_e32 v133, 9, v133
	v_lshl_add_u32 v133, v131, 5, v133
	v_add_u32_e32 v133, 0x21000, v133
	ds_read_b32 v132, v133
	ds_read_b32 v130, v133 offset:4
	ds_read_b32 v148, v133 offset:8
	ds_read_b32 v146, v133 offset:12
	ds_read_b32 v164, v133 offset:16
	ds_read_b32 v162, v133 offset:20
	ds_read_b32 v192, v133 offset:24
	ds_read_b32 v190, v133 offset:28
	s_waitcnt vmcnt(0) lgkmcnt(0)
	s_branch .LBB0_516
